# scan chunk-boundary address calc moved to scalar regs (on top of hand-written phase 3)
# speedup vs baseline: 1.0796x; 1.0055x over previous
; DI void scan_task(const Params& P, int sb, unsigned char* lds) {
;     ...
;     for (int c = 0; c < NCH; ++c) {
;       const float* cb = buf + (c & 1) * (CH * SREC);
;       const float* vrow = vtb + (c & 1) * (16 * CH) + rowl * CH;
;       float* yb = ybuf + (c & 1) * (CH * 16);
;       StepOps cur, nxt, nx2, nx3;
;       ld_ops(cur, cb, q4);
;       ld_ops(nxt, cb + SREC, q4);
;       ld_ops(nx2, cb + 2 * SREC, q4);
.LBB0_1197:
	s_and_b32 s3, s0, 1
	s_lshl_b32 s2, s3, 11
	s_mul_i32 s3, s3, 0xb000
	v_lshl_or_b32 v56, v68, 2, s3
	v_add_u32_e32 v72, s3, v69
	ds_read_b128 v[0:3], v56
	ds_read_b128 v[4:7], v56 offset:256
	s_waitcnt vmcnt(1)
	ds_read_b128 v[8:11], v56 offset:512
	ds_read_b128 v[12:15], v56 offset:768
	ds_read_b128 v[16:19], v56 offset:1024
	ds_read_b128 v[20:23], v56 offset:1408
	ds_read_b128 v[24:27], v56 offset:1664
	ds_read_b128 v[36:39], v56 offset:1920
	ds_read_b128 v[28:31], v56 offset:2176
	ds_read_b128 v[32:35], v56 offset:2432
	ds_read_b128 v[40:43], v56 offset:2816
	ds_read_b128 v[44:47], v56 offset:3072
	ds_read_b128 v[48:51], v56 offset:3328
	ds_read_b128 v[52:55], v56 offset:3584
	ds_read_b128 v[56:59], v56 offset:3840
	v_add_u32_e32 v73, s2, v70
	v_or_b32_e32 v74, s2, v71
	s_mov_b32 s3, 8
